# next-layer ffn1/w_in weight conversion folded into the RG-LRU summary pass (2 source rows loaded per LRU item, convert+store every 4th item) instead of a separate loop after it
# speedup vs baseline: 1.0139x; 1.0046x over previous
.LBB0_120:
	s_abs_i32 s8, s87
	v_cvt_f32_u32_e32 v0, s8
	s_add_i32 s0, s87, 0xbff
	s_sub_i32 s1, 0xfffff401, s87
	s_xor_b32 s4, s0, s87
	v_rcp_iflag_f32_e32 v0, v0
	s_max_i32 s0, s0, s1
	s_sub_i32 s1, 0, s8
	s_ashr_i32 s4, s4, 31
	v_mul_f32_e32 v0, 0x4f7ffffe, v0
	v_cvt_u32_f32_e32 v0, v0
	v_readlane_b32 s26, v242, 32
	v_readlane_b32 s90, v242, 34
	v_readlane_b32 s27, v242, 33
	v_readfirstlane_b32 s9, v0
	s_mul_i32 s1, s1, s9
	s_mul_hi_u32 s1, s9, s1
	s_add_i32 s9, s9, s1
	s_mul_hi_u32 s1, s0, s9
	s_mul_i32 s5, s1, s8
	s_sub_i32 s0, s0, s5
	s_add_i32 s6, s1, 1
	s_sub_i32 s5, s0, s8
	s_cmp_ge_u32 s0, s8
	s_cselect_b32 s1, s6, s1
	s_cselect_b32 s0, s5, s0
	s_add_i32 s5, s1, 1
	s_cmp_ge_u32 s0, s8
	s_cselect_b32 s0, s5, s1
	s_xor_b32 s0, s0, s4
	s_sub_i32 s0, s0, s4
	s_mul_i32 s10, s0, s3
	s_add_i32 s0, s10, s0
	s_min_i32 s11, s0, 0xc00
	s_cmp_ge_i32 s10, s11
	v_readlane_b32 s91, v242, 35
	v_readlane_b32 s38, v242, 57
	s_barrier
	v_readlane_b32 s39, v242, 58
	s_cbranch_scc1 .LBB0_130
	v_readlane_b32 s4, v242, 50
	s_mul_i32 s0, s4, 0x2c00
	s_add_i32 s0, s0, 0
	v_readlane_b32 s1, v242, 17
	v_mov_b32_e32 v0, s0
	s_waitcnt vmcnt(6)
	v_lshl_add_u32 v69, v132, 1, s0
	v_add_u32_e32 v67, s1, v141
	s_movk_i32 s1, 0x90
	v_mad_u32_u24 v3, v142, s1, v0
	s_movk_i32 s1, 0xff74
	v_add_u32_e32 v70, s0, v141
	s_ashr_i32 s0, s10, 5
	v_mad_i32_i24 v7, v142, s1, v3
	s_mul_hi_i32 s1, s0, 0x2aaaaaab
	s_lshl_b32 s12, s4, 4
	s_lshl_b32 s14, s4, 9
	s_lshr_b32 s4, s1, 31
	s_ashr_i32 s1, s1, 1
	s_add_i32 s1, s1, s4
	s_add_i32 s13, s12, -3
	s_mul_i32 s5, s1, 0x1e00000
	s_mul_hi_i32 s4, s1, 0x1e00000
	s_add_u32 s5, s33, s5
	s_mul_i32 s1, s1, -12
	s_addc_u32 s4, s68, s4
	s_add_i32 s1, s1, s0
	s_lshl_b32 s0, s1, 6
	s_ashr_i32 s1, s0, 31
	s_lshl_b64 s[0:1], s[0:1], 1
	s_add_u32 s0, s5, s0
	s_addc_u32 s1, s4, s1
	s_lshl_b32 s15, s10, 7
	v_lshlrev_b32_e32 v128, 1, v132
	s_and_b32 s4, s15, 0xf80
	v_lshl_add_u64 v[64:65], s[0:1], 0, v[128:129]
	s_mov_b64 s[0:1], 0x1200
	s_add_i32 s5, s4, s13
	v_lshl_add_u64 v[64:65], v[64:65], 0, s[0:1]
	s_max_i32 s0, s5, 0xffffffee
	s_add_i32 s0, s0, 18
	v_mad_u64_u32 v[72:73], s[0:1], s0, v165, v[64:65]
	s_max_i32 s0, s5, 0xffffffef
	s_add_i32 s0, s0, 17
	v_mad_u64_u32 v[74:75], s[0:1], s0, v165, v[64:65]
	s_max_i32 s0, s5, -16
	s_add_i32 s0, s0, 16
	v_mad_u64_u32 v[76:77], s[0:1], s0, v165, v[64:65]
	s_max_i32 s0, s5, -15
	s_add_i32 s0, s0, 15
	v_mad_u64_u32 v[78:79], s[0:1], s0, v165, v[64:65]
	s_max_i32 s0, s5, -14
	s_add_i32 s0, s0, 14
	s_waitcnt vmcnt(4)
	v_mad_u64_u32 v[80:81], s[0:1], s0, v165, v[64:65]
	s_max_i32 s0, s5, -13
	s_add_i32 s0, s0, 13
	v_mad_u64_u32 v[82:83], s[0:1], s0, v165, v[64:65]
	s_max_i32 s0, s5, -12
	s_add_i32 s0, s0, 12
	v_mad_u64_u32 v[84:85], s[0:1], s0, v165, v[64:65]
	s_max_i32 s0, s5, -11
	s_add_i32 s0, s0, 11
	v_mad_u64_u32 v[86:87], s[0:1], s0, v165, v[64:65]
	s_max_i32 s0, s5, -10
	s_add_i32 s0, s0, 10
	v_mad_u64_u32 v[88:89], s[0:1], s0, v165, v[64:65]
	s_max_i32 s0, s5, -9
	s_add_i32 s0, s0, 9
	v_mad_u64_u32 v[90:91], s[0:1], s0, v165, v[64:65]
	s_max_i32 s0, s5, -8
	s_add_i32 s0, s0, 8
	v_mad_u64_u32 v[92:93], s[0:1], s0, v165, v[64:65]
	s_max_i32 s0, s5, -7
	s_add_i32 s0, s0, 7
	v_mad_u64_u32 v[94:95], s[0:1], s0, v165, v[64:65]
	s_max_i32 s0, s5, -6
	s_add_i32 s0, s0, 6
	v_mad_u64_u32 v[96:97], s[0:1], s0, v165, v[64:65]
	s_max_i32 s0, s5, -5
	s_add_i32 s0, s0, 5
	v_mad_u64_u32 v[98:99], s[0:1], s0, v165, v[64:65]
	s_max_i32 s0, s5, -4
	s_add_i32 s0, s0, 4
	v_mad_u64_u32 v[100:101], s[0:1], s0, v165, v[64:65]
	s_add_i32 s4, s4, s12
	s_max_i32 s0, s4, 0
	v_mad_u64_u32 v[102:103], s[0:1], s0, v165, v[64:65]
	s_or_b32 s0, s5, 2
	s_max_i32 s0, s0, 0
	v_mad_u64_u32 v[104:105], s[0:1], s0, v165, v[64:65]
	s_max_i32 s0, s5, -1
	s_add_i32 s0, s0, 1
	v_mad_u64_u32 v[106:107], s[0:1], s0, v165, v[64:65]
	s_max_i32 s0, s5, 0
	s_nop 0
	v_mad_u64_u32 v[64:65], s[0:1], s0, v165, v[64:65]
	global_load_ushort v137, v[64:65], off
	global_load_ushort v136, v[106:107], off
	global_load_ushort v135, v[104:105], off
	global_load_ushort v134, v[102:103], off
	global_load_ushort v127, v[100:101], off
	global_load_ushort v126, v[98:99], off
	global_load_ushort v125, v[96:97], off
	global_load_ushort v124, v[94:95], off
	global_load_ushort v123, v[92:93], off
	global_load_ushort v122, v[90:91], off
	global_load_ushort v121, v[88:89], off
	global_load_ushort v120, v[86:87], off
	global_load_ushort v119, v[84:85], off
	global_load_ushort v116, v[82:83], off
	global_load_ushort v115, v[80:81], off
	global_load_ushort v114, v[78:79], off
	global_load_ushort v113, v[76:77], off
	global_load_ushort v118, v[74:75], off
	global_load_ushort v117, v[72:73], off
	v_lshlrev_b32_e32 v1, 9, v131
	v_or_b32_e32 v9, 0x800, v1
	v_or_b32_e32 v11, 48, v132
	v_or_b32_e32 v13, 0x840, v1
	v_or_b32_e32 v15, 0x880, v1
	v_or_b32_e32 v16, 0x8c0, v1
	v_or_b32_e32 v17, 0x900, v1
	v_or_b32_e32 v18, 0x940, v1
	v_or_b32_e32 v19, 0x980, v1
	v_or_b32_e32 v21, 0x9c0, v1
	v_or_b32_e32 v23, 16, v142
	v_or_b32_e32 v25, 32, v142
	v_and_b32_e32 v5, 48, v169
	v_or_b32_e32 v0, v9, v11
	v_or_b32_e32 v2, v1, v142
	v_or_b32_e32 v4, v9, v142
	v_or_b32_e32 v6, v13, v142
	v_or_b32_e32 v8, v15, v142
	v_or_b32_e32 v10, v16, v142
	v_or_b32_e32 v12, v17, v142
	v_or_b32_e32 v14, v18, v142
	v_or_b32_e32 v30, v19, v142
	v_or_b32_e32 v68, v21, v142
	v_or_b32_e32 v66, v9, v23
	v_or_b32_e32 v62, v13, v23
	v_or_b32_e32 v60, v15, v23
	v_or_b32_e32 v58, v16, v23
	v_or_b32_e32 v56, v17, v23
	v_or_b32_e32 v54, v18, v23
	v_or_b32_e32 v52, v19, v23
	v_or_b32_e32 v50, v21, v23
	v_or_b32_e32 v48, v9, v25
	v_or_b32_e32 v46, v13, v25
	v_or_b32_e32 v44, v15, v25
	v_or_b32_e32 v42, v16, v25
	v_or_b32_e32 v40, v17, v25
	v_or_b32_e32 v38, v18, v25
	v_or_b32_e32 v36, v19, v25
	v_or_b32_e32 v34, v21, v25
	v_or_b32_e32 v32, v1, v11
	v_or_b32_e32 v28, v13, v11
	v_or_b32_e32 v26, v15, v11
	v_or_b32_e32 v24, v16, v11
	v_or_b32_e32 v22, v17, v11
	v_or_b32_e32 v20, v18, v11
	v_or_b32_e32 v18, v19, v11
	v_or_b32_e32 v16, v21, v11
	v_mul_u32_u24_e32 v9, 0x440, v131
	v_or_b32_e32 v80, v1, v23
	v_or_b32_e32 v88, v1, v25
	s_mov_b32 s16, -1
	v_mov_b32_e32 v64, v129
	v_mov_b32_e32 v65, v129
	v_mov_b32_e32 v81, 0
	v_lshlrev_b32_e32 v71, 2, v2
	v_lshlrev_b32_e32 v72, 2, v4
	v_lshlrev_b32_e32 v73, 2, v6
	v_lshlrev_b32_e32 v74, 2, v8
	v_lshlrev_b32_e32 v75, 2, v10
	v_lshlrev_b32_e32 v76, 2, v12
	v_lshlrev_b32_e32 v77, 2, v14
	v_lshlrev_b32_e32 v78, 2, v30
	v_lshlrev_b32_e32 v68, 2, v68
	v_lshlrev_b32_e32 v79, 2, v80
	v_lshlrev_b32_e32 v66, 2, v66
	v_lshlrev_b32_e32 v80, 2, v62
	v_lshlrev_b32_e32 v82, 2, v60
	v_lshlrev_b32_e32 v83, 2, v58
	v_lshlrev_b32_e32 v84, 2, v56
	v_lshlrev_b32_e32 v85, 2, v54
	v_lshlrev_b32_e32 v86, 2, v52
	v_lshlrev_b32_e32 v87, 2, v50
	v_lshlrev_b32_e32 v88, 2, v88
	v_lshlrev_b32_e32 v89, 2, v48
	v_lshlrev_b32_e32 v90, 2, v46
	v_lshlrev_b32_e32 v91, 2, v44
	v_lshlrev_b32_e32 v92, 2, v42
	v_lshlrev_b32_e32 v93, 2, v40
	v_lshlrev_b32_e32 v94, 2, v38
	v_lshlrev_b32_e32 v95, 2, v36
	v_lshlrev_b32_e32 v96, 2, v34
	v_lshlrev_b32_e32 v97, 2, v32
	v_lshlrev_b32_e32 v98, 2, v0
	v_lshlrev_b32_e32 v99, 2, v28
	v_lshlrev_b32_e32 v100, 2, v26
	v_lshlrev_b32_e32 v101, 2, v24
	v_lshlrev_b32_e32 v102, 2, v22
	v_lshlrev_b32_e32 v103, 2, v20
	v_lshlrev_b32_e32 v104, 2, v18
	v_lshlrev_b32_e32 v105, 2, v16
	v_add_u32_e32 v106, v3, v5
	v_add_u32_e32 v107, v7, v9
	v_mov_b32_e32 v108, 0
	v_mov_b32_e32 v109, 0
	v_mov_b32_e32 v110, 0
	v_mov_b32_e32 v111, 0
	v_mov_b32_e32 v112, 0
	s_mov_b32 s22, 0
	v_writelane_b32 v242, s22, 62
	s_mov_b32 s41, -1
	s_branch .LBB0_123

.LBB0_127:
	v_readlane_b32 s22, v242, 62
	s_and_b32 s40, s22, 3
	s_cmp_lg_u32 s40, 0
	s_cbranch_scc1 .Lcvf_rows
	s_lshr_b32 s22, s22, 2
	s_mov_b32 s41, -1
	s_cmp_gt_i32 s38, 2
	s_cbranch_scc1 .Lcvf_a_done
	v_readlane_b32 s40, v243, 0
	v_readlane_b32 s42, v242, 50
	s_lshl_b32 s40, s40, 3
	s_add_i32 s40, s40, s42
	s_mul_i32 s42, s22, s86
	s_add_i32 s40, s40, s42
	s_cmp_ge_i32 s40, 0x1800
	s_cbranch_scc1 .Lcvf_a_done
	s_add_i32 s22, s38, 1
	v_readlane_b32 s48, v242, 44
	v_readlane_b32 s49, v242, 45
	s_cmp_ge_i32 s40, 0x1080
	s_cbranch_scc1 .Lcvf_win
	s_cmp_ge_i32 s40, 0xb00
	s_cbranch_scc1 .Lcvf_down
	s_mov_b32 s41, 1
	v_readlane_b32 s46, v242, 2
	v_readlane_b32 s47, v242, 3
	s_cmp_ge_i32 s40, 0x580
	s_cbranch_scc0 .Lcvf_gu
	s_mov_b32 s41, 2
	s_add_i32 s40, s40, 0xfffffa80
	v_readlane_b32 s46, v242, 4
	v_readlane_b32 s47, v242, 5
.Lcvf_gu:
	s_movk_i32 s42, 0x400
	s_movk_i32 s43, 0xb00
	s_mul_i32 s44, s40, 0x2e8c
	s_lshr_b32 s44, s44, 20
	s_mul_i32 s45, s44, 0x58
	s_sub_i32 s45, s40, s45
	s_mul_i32 s40, s22, 0xb00000
	s_add_u32 s46, s46, s40
	s_addc_u32 s47, s47, 0
	s_lshl_b32 s40, s44, 6
	s_lshl_b32 s45, s45, 5
	v_readlane_b32 s44, v242, 0
	s_nop 0
	s_lshl_b32 s22, s22, 12
	s_add_u32 s44, s44, s22
	v_readlane_b32 s22, v242, 1
	s_nop 0
	s_addc_u32 s22, s22, 0
	s_branch .Lcvf_issue
.Lcvf_down:
	s_mov_b32 s41, 0
	s_add_i32 s40, s40, 0xfffff500
	v_readlane_b32 s46, v242, 6
	v_readlane_b32 s47, v242, 7
	s_movk_i32 s42, 0xb00
	s_movk_i32 s43, 0x400
	s_lshr_b32 s44, s40, 5
	s_and_b32 s45, s40, 31
	s_mul_i32 s40, s22, 0xb00000
	s_add_u32 s46, s46, s40
	s_addc_u32 s47, s47, 0
	s_add_u32 s48, s48, 0xb00000
	s_addc_u32 s49, s49, 0
	s_lshl_b32 s40, s44, 6
	s_lshl_b32 s45, s45, 5
	s_mov_b32 s44, 0
	s_mov_b32 s22, 0
	s_branch .Lcvf_issue
.Lcvf_win:
	s_mov_b32 s41, 0
	s_add_i32 s40, s40, 0xffffef80
	v_readlane_b32 s46, v242, 10
	v_readlane_b32 s47, v242, 11
	s_movk_i32 s42, 0x400
	s_movk_i32 s43, 0xf00
	s_mul_i32 s44, s40, 0x2223
	s_lshr_b32 s44, s44, 20
	s_mul_i32 s45, s44, 0x78
	s_sub_i32 s45, s40, s45
	s_mul_i32 s40, s22, 0xf00000
	s_add_u32 s46, s46, s40
	s_addc_u32 s47, s47, 0
	s_add_u32 s48, s48, 0x1080000
	s_addc_u32 s49, s49, 0
	s_lshl_b32 s40, s44, 6
	s_lshl_b32 s45, s45, 5
	v_readlane_b32 s44, v242, 8
	s_nop 0
	s_lshl_b32 s22, s22, 12
	s_add_u32 s44, s44, s22
	v_readlane_b32 s22, v242, 9
	s_nop 0
	s_addc_u32 s22, s22, 0
.Lcvf_issue:
	v_and_b32_e32 v226, 7, v167
	v_lshrrev_b32_e32 v227, 3, v167
	v_lshl_add_u32 v226, v226, 3, s40
	v_lshl_add_u32 v227, v227, 2, s45
	s_lshl_b32 s43, s43, 2
	v_lshlrev_b32_e32 v228, 2, v227
	v_mad_u32_u24 v228, v226, s43, v228
	s_mov_b32 s45, s22
	s_cmp_eq_u64 s[44:45], 0
	s_cbranch_scc1 .Lcvf_rows
	v_lshlrev_b32_e32 v229, 2, v226
	global_load_dwordx4 v[218:221], v229, s[44:45]
	global_load_dwordx4 v[222:225], v229, s[44:45] offset:16
.Lcvf_rows:
	s_cmp_lt_i32 s41, 0
	s_cbranch_scc1 .Lcvf_a_done
	v_readlane_b32 s22, v242, 62
	s_and_b32 s22, s22, 3
	s_cmp_eq_u32 s22, 0
	s_cbranch_scc0 .Lcvf_q1
	global_load_dwordx4 v[186:189], v228, s[46:47] nt
	v_add_u32_e32 v228, s43, v228
	global_load_dwordx4 v[190:193], v228, s[46:47] nt
	v_add_u32_e32 v228, s43, v228
	s_branch .Lcvf_a_done
.Lcvf_q1:
	s_cmp_eq_u32 s22, 1
	s_cbranch_scc0 .Lcvf_q2
	global_load_dwordx4 v[194:197], v228, s[46:47] nt
	v_add_u32_e32 v228, s43, v228
	global_load_dwordx4 v[198:201], v228, s[46:47] nt
	v_add_u32_e32 v228, s43, v228
	s_branch .Lcvf_a_done
.Lcvf_q2:
	s_cmp_eq_u32 s22, 2
	s_cbranch_scc0 .Lcvf_q3
	global_load_dwordx4 v[202:205], v228, s[46:47] nt
	v_add_u32_e32 v228, s43, v228
	global_load_dwordx4 v[206:209], v228, s[46:47] nt
	v_add_u32_e32 v228, s43, v228
	s_branch .Lcvf_a_done
.Lcvf_q3:
	global_load_dwordx4 v[210:213], v228, s[46:47] nt
	v_add_u32_e32 v228, s43, v228
	global_load_dwordx4 v[214:217], v228, s[46:47] nt
.Lcvf_a_done:
	s_and_b32 s17, s15, 0xf80
	s_add_i32 s0, s17, s12
	s_cmp_gt_i32 s0, 2
	v_lshlrev_b32_e32 v137, 16, v137
	s_cselect_b64 vcc, -1, 0
	s_cmp_gt_i32 s0, 1
	v_cndmask_b32_e32 v137, 0, v137, vcc
	v_lshlrev_b32_e32 v136, 16, v136
	s_cselect_b64 vcc, -1, 0
	s_cmp_gt_i32 s0, 0
	v_cndmask_b32_e32 v136, 0, v136, vcc
	v_lshlrev_b32_e32 v135, 16, v135
	s_cselect_b64 vcc, -1, 0
	s_cmp_gt_i32 s0, -1
	v_cndmask_b32_e32 v135, 0, v135, vcc
	v_lshlrev_b32_e32 v134, 16, v134
	s_cselect_b64 vcc, -1, 0
	s_cmp_gt_i32 s0, -2
	v_cndmask_b32_e32 v134, 0, v134, vcc
	v_lshlrev_b32_e32 v127, 16, v127
	s_cselect_b64 vcc, -1, 0
	s_cmp_gt_i32 s0, -3
	v_cndmask_b32_e32 v170, 0, v127, vcc
	v_lshlrev_b32_e32 v126, 16, v126
	s_cselect_b64 vcc, -1, 0
	s_cmp_gt_i32 s0, -4
	v_cndmask_b32_e32 v171, 0, v126, vcc
	v_lshlrev_b32_e32 v125, 16, v125
	s_cselect_b64 vcc, -1, 0
	s_cmp_gt_i32 s0, -5
	v_cndmask_b32_e32 v172, 0, v125, vcc
	v_lshlrev_b32_e32 v124, 16, v124
	s_cselect_b64 vcc, -1, 0
	s_cmp_gt_i32 s0, -6
	v_cndmask_b32_e32 v173, 0, v124, vcc
	v_lshlrev_b32_e32 v123, 16, v123
	s_cselect_b64 vcc, -1, 0
	s_cmp_gt_i32 s0, -7
	v_cndmask_b32_e32 v174, 0, v123, vcc
	v_lshlrev_b32_e32 v122, 16, v122
	s_cselect_b64 vcc, -1, 0
	s_cmp_gt_i32 s0, -8
	v_cndmask_b32_e32 v175, 0, v122, vcc
	v_lshlrev_b32_e32 v121, 16, v121
	s_cselect_b64 vcc, -1, 0
	s_cmp_gt_i32 s0, -9
	v_cndmask_b32_e32 v176, 0, v121, vcc
	v_lshlrev_b32_e32 v120, 16, v120
	s_cselect_b64 vcc, -1, 0
	s_cmp_gt_i32 s0, -10
	v_cndmask_b32_e32 v177, 0, v120, vcc
	v_lshlrev_b32_e32 v119, 16, v119
	s_cselect_b64 vcc, -1, 0
	s_cmp_gt_i32 s0, -11
	v_cndmask_b32_e32 v178, 0, v119, vcc
	v_lshlrev_b32_e32 v116, 16, v116
	s_cselect_b64 vcc, -1, 0
	s_cmp_gt_i32 s0, -12
	v_cndmask_b32_e32 v179, 0, v116, vcc
	v_lshlrev_b32_e32 v115, 16, v115
	s_cselect_b64 vcc, -1, 0
	s_cmp_gt_i32 s0, -13
	v_cndmask_b32_e32 v180, 0, v115, vcc
	v_lshlrev_b32_e32 v114, 16, v114
	s_cselect_b64 vcc, -1, 0
	s_cmp_gt_i32 s0, -14
	v_cndmask_b32_e32 v181, 0, v114, vcc
	v_lshlrev_b32_e32 v113, 16, v113
	s_cselect_b64 vcc, -1, 0
	s_cmp_gt_i32 s0, -15
	v_fma_f32 v185, v137, v81, v111
	v_cndmask_b32_e32 v182, 0, v113, vcc
	v_lshlrev_b32_e32 v113, 16, v118
	s_cselect_b64 vcc, -1, 0
	s_cmp_gt_i32 s0, -16
	v_fmac_f32_e32 v185, v136, v108
	v_fma_f32 v127, v136, v81, v111
	v_cndmask_b32_e32 v183, 0, v113, vcc
	v_lshlrev_b32_e32 v113, 16, v117
	s_cselect_b64 vcc, -1, 0
	v_fmac_f32_e32 v185, v135, v109
	v_fmac_f32_e32 v127, v135, v108
	v_fma_f32 v126, v135, v81, v111
	v_cndmask_b32_e32 v184, 0, v113, vcc
	v_fmac_f32_e32 v185, v134, v110
	v_cvt_pk_bf16_f32 v113, v185, v129
	v_fmac_f32_e32 v127, v134, v109
	v_fmac_f32_e32 v126, v134, v108
	v_fma_f32 v125, v134, v81, v111
	ds_write_b16 v69, v113
	v_fmac_f32_e32 v127, v170, v110
	v_cvt_pk_bf16_f32 v113, v127, v129
	v_fmac_f32_e32 v126, v170, v109
	v_fmac_f32_e32 v125, v170, v108
	v_fma_f32 v124, v170, v81, v111
	ds_write_b16 v69, v113 offset:144
	v_fmac_f32_e32 v126, v171, v110
	v_cvt_pk_bf16_f32 v113, v126, v129
	v_fmac_f32_e32 v125, v171, v109
	v_fmac_f32_e32 v124, v171, v108
	v_fma_f32 v123, v171, v81, v111
	ds_write_b16 v69, v113 offset:288
	v_fmac_f32_e32 v125, v172, v110
	v_cvt_pk_bf16_f32 v113, v125, v129
	v_fmac_f32_e32 v124, v172, v109
	v_fmac_f32_e32 v123, v172, v108
	v_fma_f32 v122, v172, v81, v111
	ds_write_b16 v69, v113 offset:432
	v_fmac_f32_e32 v124, v173, v110
	v_cvt_pk_bf16_f32 v113, v124, v129
	v_fmac_f32_e32 v123, v173, v109
	v_fmac_f32_e32 v122, v173, v108
	v_fma_f32 v121, v173, v81, v111
	ds_write_b16 v69, v113 offset:576
	v_fmac_f32_e32 v123, v174, v110
	v_cvt_pk_bf16_f32 v113, v123, v129
	v_fmac_f32_e32 v122, v174, v109
	v_fmac_f32_e32 v121, v174, v108
	v_fma_f32 v120, v174, v81, v111
	ds_write_b16 v69, v113 offset:720
	v_fmac_f32_e32 v122, v175, v110
	v_cvt_pk_bf16_f32 v113, v122, v129
	v_fmac_f32_e32 v121, v175, v109
	v_fmac_f32_e32 v120, v175, v108
	v_fma_f32 v119, v175, v81, v111
	ds_write_b16 v69, v113 offset:864
	v_fmac_f32_e32 v121, v176, v110
	v_cvt_pk_bf16_f32 v113, v121, v129
	v_fmac_f32_e32 v120, v176, v109
	v_fmac_f32_e32 v119, v176, v108
	v_fma_f32 v118, v176, v81, v111
	ds_write_b16 v69, v113 offset:1008
	v_fmac_f32_e32 v120, v177, v110
	v_cvt_pk_bf16_f32 v113, v120, v129
	v_fmac_f32_e32 v119, v177, v109
	v_fmac_f32_e32 v118, v177, v108
	v_fma_f32 v117, v177, v81, v111
	ds_write_b16 v69, v113 offset:1152
	v_fmac_f32_e32 v119, v178, v110
	v_cvt_pk_bf16_f32 v113, v119, v129
	v_fmac_f32_e32 v118, v178, v109
	v_fmac_f32_e32 v117, v178, v108
	v_fma_f32 v116, v178, v81, v111
	ds_write_b16 v69, v113 offset:1296
	v_fmac_f32_e32 v118, v179, v110
	v_cvt_pk_bf16_f32 v113, v118, v129
	v_fmac_f32_e32 v117, v179, v109
	v_fmac_f32_e32 v116, v179, v108
	v_fma_f32 v115, v179, v81, v111
	ds_write_b16 v69, v113 offset:1440
	v_fmac_f32_e32 v117, v180, v110
	v_cvt_pk_bf16_f32 v113, v117, v129
	v_fmac_f32_e32 v116, v180, v109
	v_fmac_f32_e32 v115, v180, v108
	v_fma_f32 v114, v180, v81, v111
	ds_write_b16 v69, v113 offset:1584
	v_fmac_f32_e32 v116, v181, v110
	v_cvt_pk_bf16_f32 v113, v116, v129
	v_fmac_f32_e32 v115, v181, v109
	v_fmac_f32_e32 v114, v181, v108
	ds_write_b16 v69, v113 offset:1728
	v_fmac_f32_e32 v115, v182, v110
	v_cvt_pk_bf16_f32 v113, v115, v129
	v_fmac_f32_e32 v114, v182, v109
	ds_write_b16 v69, v113 offset:1872
	v_fmac_f32_e32 v114, v183, v110
	v_cvt_pk_bf16_f32 v113, v114, v129
	ds_write_b16 v69, v113 offset:2016
	v_fma_f32 v113, v181, v81, v111
	v_fmac_f32_e32 v113, v182, v108
	v_fmac_f32_e32 v113, v183, v109
	v_fmac_f32_e32 v113, v184, v110
	v_cvt_pk_bf16_f32 v134, v113, v129
	ds_write_b16 v69, v134 offset:2160
	s_waitcnt lgkmcnt(0)
	ds_read_b128 v[134:137], v106
	ds_read_b128 v[170:173], v106 offset:64
	s_waitcnt lgkmcnt(1)
	v_mfma_f32_16x16x32_bf16 v[174:177], v[134:137], v[0:3], 0
	v_add_u32_e32 v182, 0x800, v107
	v_add_u32_e32 v183, 0xc00, v107
	v_mfma_f32_16x16x32_bf16 v[178:181], v[134:137], v[8:11], 0
	s_waitcnt lgkmcnt(0)
	v_mfma_f32_16x16x32_bf16 v[174:177], v[170:173], v[4:7], v[174:177]
	v_mfma_f32_16x16x32_bf16 v[178:181], v[170:173], v[12:15], v[178:181]
	s_nop 7
	ds_write2_b32 v182, v174, v178 offset0:64 offset1:80
	ds_write2_b32 v182, v175, v179 offset0:132 offset1:148
	ds_write2_b32 v182, v176, v180 offset0:200 offset1:216
	ds_write2_b32 v183, v177, v181 offset0:12 offset1:28
	v_mfma_f32_16x16x32_bf16 v[174:177], v[134:137], v[16:19], 0
	v_mfma_f32_16x16x32_bf16 v[178:181], v[134:137], v[24:27], 0
	v_mfma_f32_16x16x32_bf16 v[174:177], v[170:173], v[20:23], v[174:177]
	v_mfma_f32_16x16x32_bf16 v[178:181], v[170:173], v[28:31], v[178:181]
	s_nop 7
	ds_write2_b32 v182, v174, v178 offset0:96 offset1:112
	ds_write2_b32 v182, v175, v179 offset0:164 offset1:180
	ds_write2_b32 v182, v176, v180 offset0:232 offset1:248
	ds_write2_b32 v183, v177, v181 offset0:44 offset1:60
	v_mfma_f32_16x16x32_bf16 v[174:177], v[134:137], v[32:35], 0
	v_add_u32_e32 v182, 0x1800, v107
	v_mfma_f32_16x16x32_bf16 v[178:181], v[134:137], v[40:43], 0
	v_mfma_f32_16x16x32_bf16 v[174:177], v[170:173], v[36:39], v[174:177]
	v_mfma_f32_16x16x32_bf16 v[178:181], v[170:173], v[44:47], v[178:181]
	s_nop 7
	ds_write2_b32 v182, v174, v178 offset0:128 offset1:144
	ds_write2_b32 v182, v175, v179 offset0:196 offset1:212
	v_add_u32_e32 v178, 0x1c00, v107
	ds_write2_b32 v178, v176, v180 offset0:8 offset1:24
	ds_write2_b32 v178, v177, v181 offset0:76 offset1:92
	v_mfma_f32_16x16x32_bf16 v[174:177], v[134:137], v[48:51], 0
	v_mfma_f32_16x16x32_bf16 v[134:137], v[134:137], v[56:59], 0
	v_mfma_f32_16x16x32_bf16 v[174:177], v[170:173], v[52:55], v[174:177]
	v_mfma_f32_16x16x32_bf16 v[134:137], v[170:173], v[60:63], v[134:137]
	s_nop 7
	ds_write2_b32 v182, v174, v134 offset0:160 offset1:176
	ds_write2_b32 v182, v175, v135 offset0:228 offset1:244
	ds_write2_b32 v178, v176, v136 offset0:40 offset1:56
	ds_write2_b32 v178, v177, v137 offset0:108 offset1:124
	s_waitcnt lgkmcnt(0)
	v_add_u32_e32 v134, 0x800, v70
	ds_read2_b32 v[134:135], v134 offset0:64 offset1:132
	v_add_u32_e32 v136, 0x1800, v70
	ds_read2_b32 v[136:137], v136 offset0:128 offset1:196
	s_waitcnt lgkmcnt(1)
	v_fmamk_f32 v134, v134, 0xbfb8aa3b, v112
	v_exp_f32_e32 v134, v134
	v_fmamk_f32 v135, v135, 0xbfb8aa3b, v112
	v_exp_f32_e32 v135, v135
	s_waitcnt lgkmcnt(0)
	v_fmamk_f32 v136, v136, 0xbfb8aa3b, v65
	v_add_f32_e32 v134, 1.0, v134
	v_rcp_f32_e32 v134, v134
	v_add_f32_e32 v135, 1.0, v135
	v_exp_f32_e32 v136, v136
	v_rcp_f32_e32 v135, v135
	v_mul_f32_e32 v134, v64, v134
	v_exp_f32_e32 v134, v134
	v_add_f32_e32 v136, 1.0, v136
	v_mul_f32_e32 v135, v64, v135
	v_rcp_f32_e32 v136, v136
	v_fma_f32 v170, -v134, v134, 1.0
	v_max_f32_e32 v170, 0, v170
	v_exp_f32_e32 v135, v135
	s_nop 0
	v_sqrt_f32_e32 v170, v170
	s_nop 0
	v_fmamk_f32 v137, v137, 0xbfb8aa3b, v65
	v_exp_f32_e32 v137, v137
	s_nop 0
	v_add_f32_e32 v137, 1.0, v137
	v_rcp_f32_e32 v137, v137
	s_nop 0
	v_mul_f32_e32 v136, v136, v170
	v_fma_f32 v170, -v135, v135, 1.0
	v_max_f32_e32 v170, 0, v170
	v_mul_f32_e32 v136, v185, v136
	v_sqrt_f32_e32 v170, v170
	s_nop 0
	v_fmac_f32_e32 v136, 0, v134
	v_mul_f32_e32 v137, v137, v170
	v_mul_f32_e32 v127, v127, v137
	v_mul_f32_e32 v170, v134, v135
	v_add_u32_e32 v134, 0xa00, v70
	v_fmac_f32_e32 v127, v135, v136
	ds_read2_b32 v[134:135], v134 offset0:72 offset1:140
	v_add_u32_e32 v171, 0x1c00, v70
	ds_read2_b32 v[136:137], v171 offset0:8 offset1:76
	s_waitcnt lgkmcnt(1)
	v_fmamk_f32 v134, v134, 0xbfb8aa3b, v112
	v_exp_f32_e32 v134, v134
	s_waitcnt lgkmcnt(0)
	v_fmamk_f32 v136, v136, 0xbfb8aa3b, v65
	v_exp_f32_e32 v136, v136
	v_add_f32_e32 v134, 1.0, v134
	v_rcp_f32_e32 v134, v134
	v_add_f32_e32 v136, 1.0, v136
	v_rcp_f32_e32 v136, v136
	v_mul_f32_e32 v134, v64, v134
	v_exp_f32_e32 v134, v134
	s_nop 0
	v_fma_f32 v172, -v134, v134, 1.0
	v_max_f32_e32 v172, 0, v172
	v_sqrt_f32_e32 v172, v172
	s_nop 0
	v_mul_f32_e32 v136, v136, v172
	v_mul_f32_e32 v126, v126, v136
	v_fmac_f32_e32 v126, v134, v127
	v_mul_f32_e32 v127, v170, v134
	v_fmamk_f32 v134, v135, 0xbfb8aa3b, v112
	v_exp_f32_e32 v134, v134
	v_fmamk_f32 v135, v137, 0xbfb8aa3b, v65
	v_exp_f32_e32 v135, v135
	v_add_f32_e32 v134, 1.0, v134
	v_rcp_f32_e32 v134, v134
	v_add_f32_e32 v135, 1.0, v135
	v_rcp_f32_e32 v135, v135
	v_mul_f32_e32 v134, v64, v134
	v_exp_f32_e32 v134, v134
	s_nop 0
	v_fma_f32 v136, -v134, v134, 1.0
	v_max_f32_e32 v136, 0, v136
	v_sqrt_f32_e32 v136, v136
	s_nop 0
	v_mul_f32_e32 v135, v135, v136
	v_mul_f32_e32 v125, v125, v135
	v_fmac_f32_e32 v125, v134, v126
	v_add_u32_e32 v126, 0xc00, v70
	v_mul_f32_e32 v136, v127, v134
	ds_read2_b32 v[126:127], v126 offset0:80 offset1:148
	ds_read2_b32 v[134:135], v171 offset0:144 offset1:212
	s_waitcnt lgkmcnt(1)
	v_fmamk_f32 v126, v126, 0xbfb8aa3b, v112
	v_exp_f32_e32 v126, v126
	s_waitcnt lgkmcnt(0)
	v_fmamk_f32 v134, v134, 0xbfb8aa3b, v65
	v_exp_f32_e32 v134, v134
	v_add_f32_e32 v126, 1.0, v126
	v_rcp_f32_e32 v126, v126
	v_add_f32_e32 v134, 1.0, v134
	v_rcp_f32_e32 v134, v134
	v_mul_f32_e32 v126, v64, v126
	v_exp_f32_e32 v126, v126
	s_nop 0
	v_fma_f32 v137, -v126, v126, 1.0
	v_max_f32_e32 v137, 0, v137
	v_sqrt_f32_e32 v137, v137
	s_nop 0
	v_mul_f32_e32 v134, v134, v137
	v_mul_f32_e32 v124, v124, v134
	v_fmac_f32_e32 v124, v126, v125
	v_mul_f32_e32 v125, v136, v126
	v_fmamk_f32 v126, v127, 0xbfb8aa3b, v112
	v_exp_f32_e32 v126, v126
	v_fmamk_f32 v127, v135, 0xbfb8aa3b, v65
	v_exp_f32_e32 v127, v127
	v_add_f32_e32 v126, 1.0, v126
	v_rcp_f32_e32 v126, v126
	v_add_f32_e32 v127, 1.0, v127
	v_rcp_f32_e32 v127, v127
	v_mul_f32_e32 v126, v64, v126
	v_exp_f32_e32 v126, v126
	s_nop 0
	v_fma_f32 v134, -v126, v126, 1.0
	v_max_f32_e32 v134, 0, v134
	v_sqrt_f32_e32 v134, v134
	s_nop 0
	v_mul_f32_e32 v127, v127, v134
	v_mul_f32_e32 v123, v123, v127
	v_fmac_f32_e32 v123, v126, v124
	v_add_u32_e32 v124, 0xe00, v70
	v_mul_f32_e32 v134, v125, v126
	ds_read2_b32 v[124:125], v124 offset0:88 offset1:156
	v_add_u32_e32 v135, 0x2000, v70
	ds_read2_b32 v[126:127], v135 offset0:24 offset1:92
	s_waitcnt lgkmcnt(1)
	v_fmamk_f32 v124, v124, 0xbfb8aa3b, v112
	v_exp_f32_e32 v124, v124
	s_waitcnt lgkmcnt(0)
	v_fmamk_f32 v126, v126, 0xbfb8aa3b, v65
	v_exp_f32_e32 v126, v126
	v_add_f32_e32 v124, 1.0, v124
	v_rcp_f32_e32 v124, v124
	v_add_f32_e32 v126, 1.0, v126
	v_rcp_f32_e32 v126, v126
	v_mul_f32_e32 v124, v64, v124
	v_exp_f32_e32 v124, v124
	s_nop 0
	v_fma_f32 v136, -v124, v124, 1.0
	v_max_f32_e32 v136, 0, v136
	v_sqrt_f32_e32 v136, v136
	s_nop 0
	v_mul_f32_e32 v126, v126, v136
	v_mul_f32_e32 v122, v122, v126
	v_fmac_f32_e32 v122, v124, v123
	v_mul_f32_e32 v123, v134, v124
	v_fmamk_f32 v124, v125, 0xbfb8aa3b, v112
	v_exp_f32_e32 v124, v124
	v_fmamk_f32 v125, v127, 0xbfb8aa3b, v65
	v_exp_f32_e32 v125, v125
	v_add_f32_e32 v124, 1.0, v124
	v_rcp_f32_e32 v124, v124
	v_add_f32_e32 v125, 1.0, v125
	v_rcp_f32_e32 v125, v125
	v_mul_f32_e32 v124, v64, v124
	v_exp_f32_e32 v124, v124
	s_nop 0
	v_fma_f32 v126, -v124, v124, 1.0
	v_max_f32_e32 v126, 0, v126
	v_sqrt_f32_e32 v126, v126
	s_nop 0
	v_mul_f32_e32 v125, v125, v126
	v_mul_f32_e32 v121, v121, v125
	v_fmac_f32_e32 v121, v124, v122
	v_add_u32_e32 v122, 0x1000, v70
	v_mul_f32_e32 v126, v123, v124
	ds_read2_b32 v[122:123], v122 offset0:96 offset1:164
	ds_read2_b32 v[124:125], v135 offset0:160 offset1:228
	s_waitcnt lgkmcnt(1)
	v_fmamk_f32 v122, v122, 0xbfb8aa3b, v112
	v_exp_f32_e32 v122, v122
	s_waitcnt lgkmcnt(0)
	v_fmamk_f32 v124, v124, 0xbfb8aa3b, v65
	v_exp_f32_e32 v124, v124
	v_add_f32_e32 v122, 1.0, v122
	v_rcp_f32_e32 v122, v122
	v_add_f32_e32 v124, 1.0, v124
	v_rcp_f32_e32 v124, v124
	v_mul_f32_e32 v122, v64, v122
	v_exp_f32_e32 v122, v122
	s_nop 0
	v_fma_f32 v127, -v122, v122, 1.0
	v_max_f32_e32 v127, 0, v127
	v_sqrt_f32_e32 v127, v127
	s_nop 0
	v_mul_f32_e32 v124, v124, v127
	v_mul_f32_e32 v120, v120, v124
	v_fmac_f32_e32 v120, v122, v121
	v_mul_f32_e32 v121, v126, v122
	v_fmamk_f32 v122, v123, 0xbfb8aa3b, v112
	v_exp_f32_e32 v122, v122
	v_fmamk_f32 v123, v125, 0xbfb8aa3b, v65
	v_exp_f32_e32 v123, v123
	v_add_f32_e32 v122, 1.0, v122
	v_rcp_f32_e32 v122, v122
	v_add_f32_e32 v123, 1.0, v123
	v_rcp_f32_e32 v123, v123
	v_mul_f32_e32 v122, v64, v122
	v_exp_f32_e32 v122, v122
	s_nop 0
	v_fma_f32 v124, -v122, v122, 1.0
	v_max_f32_e32 v124, 0, v124
	v_sqrt_f32_e32 v124, v124
	s_nop 0
	v_mul_f32_e32 v123, v123, v124
	v_mul_f32_e32 v119, v119, v123
	v_fmac_f32_e32 v119, v122, v120
	v_add_u32_e32 v120, 0x1200, v70
	v_mul_f32_e32 v124, v121, v122
	ds_read2_b32 v[120:121], v120 offset0:104 offset1:172
	v_add_u32_e32 v125, 0x2400, v70
	ds_read2_b32 v[122:123], v125 offset0:40 offset1:108
	s_waitcnt lgkmcnt(1)
	v_fmamk_f32 v120, v120, 0xbfb8aa3b, v112
	v_exp_f32_e32 v120, v120
	s_waitcnt lgkmcnt(0)
	v_fmamk_f32 v122, v122, 0xbfb8aa3b, v65
	v_exp_f32_e32 v122, v122
	v_add_f32_e32 v120, 1.0, v120
	v_rcp_f32_e32 v120, v120
	v_add_f32_e32 v122, 1.0, v122
	v_rcp_f32_e32 v122, v122
	v_mul_f32_e32 v120, v64, v120
	v_exp_f32_e32 v120, v120
	s_nop 0
	v_fma_f32 v126, -v120, v120, 1.0
	v_max_f32_e32 v126, 0, v126
	v_sqrt_f32_e32 v126, v126
	s_nop 0
	v_mul_f32_e32 v122, v122, v126
	v_mul_f32_e32 v118, v118, v122
	v_fmac_f32_e32 v118, v120, v119
	v_mul_f32_e32 v119, v124, v120
	v_fmamk_f32 v120, v121, 0xbfb8aa3b, v112
	v_exp_f32_e32 v120, v120
	v_fmamk_f32 v121, v123, 0xbfb8aa3b, v65
	v_exp_f32_e32 v121, v121
	v_add_f32_e32 v120, 1.0, v120
	v_rcp_f32_e32 v120, v120
	v_add_f32_e32 v121, 1.0, v121
	v_rcp_f32_e32 v121, v121
	v_mul_f32_e32 v120, v64, v120
	v_exp_f32_e32 v120, v120
	s_nop 0
	v_fma_f32 v122, -v120, v120, 1.0
	v_max_f32_e32 v122, 0, v122
	v_sqrt_f32_e32 v122, v122
	s_nop 0
	v_mul_f32_e32 v121, v121, v122
	v_mul_f32_e32 v117, v117, v121
	v_fmac_f32_e32 v117, v120, v118
	v_add_u32_e32 v118, 0x1400, v70
	v_mul_f32_e32 v122, v119, v120
	ds_read2_b32 v[118:119], v118 offset0:112 offset1:180
	ds_read2_b32 v[120:121], v125 offset0:176 offset1:244
	s_waitcnt lgkmcnt(1)
	v_fmamk_f32 v118, v118, 0xbfb8aa3b, v112
	v_exp_f32_e32 v118, v118
	s_waitcnt lgkmcnt(0)
	v_fmamk_f32 v120, v120, 0xbfb8aa3b, v65
	v_exp_f32_e32 v120, v120
	v_add_f32_e32 v118, 1.0, v118
	v_rcp_f32_e32 v118, v118
	v_add_f32_e32 v120, 1.0, v120
	v_rcp_f32_e32 v120, v120
	v_mul_f32_e32 v118, v64, v118
	v_exp_f32_e32 v118, v118
	s_nop 0
	v_fma_f32 v123, -v118, v118, 1.0
	v_max_f32_e32 v123, 0, v123
	v_sqrt_f32_e32 v123, v123
	s_nop 0
	v_mul_f32_e32 v120, v120, v123
	v_mul_f32_e32 v116, v116, v120
	v_fmac_f32_e32 v116, v118, v117
	v_mul_f32_e32 v117, v122, v118
	v_fmamk_f32 v118, v119, 0xbfb8aa3b, v112
	v_exp_f32_e32 v118, v118
	v_fmamk_f32 v119, v121, 0xbfb8aa3b, v65
	v_exp_f32_e32 v119, v119
	v_add_f32_e32 v118, 1.0, v118
	v_rcp_f32_e32 v118, v118
	v_add_f32_e32 v119, 1.0, v119
	v_rcp_f32_e32 v119, v119
	v_mul_f32_e32 v118, v64, v118
	v_exp_f32_e32 v118, v118
	s_nop 0
	v_fma_f32 v120, -v118, v118, 1.0
	v_max_f32_e32 v120, 0, v120
	v_sqrt_f32_e32 v120, v120
	s_nop 0
	v_mul_f32_e32 v119, v119, v120
	v_mul_f32_e32 v115, v115, v119
	v_fmac_f32_e32 v115, v118, v116
	v_add_u32_e32 v116, 0x1600, v70
	v_mul_f32_e32 v120, v117, v118
	ds_read2_b32 v[116:117], v116 offset0:120 offset1:188
	v_add_u32_e32 v118, 0x2800, v70
	ds_read2_b32 v[118:119], v118 offset0:56 offset1:124
	s_waitcnt lgkmcnt(1)
	v_fmamk_f32 v116, v116, 0xbfb8aa3b, v112
	v_exp_f32_e32 v116, v116
	s_waitcnt lgkmcnt(0)
	v_fmamk_f32 v118, v118, 0xbfb8aa3b, v65
	v_exp_f32_e32 v118, v118
	v_add_f32_e32 v116, 1.0, v116
	v_rcp_f32_e32 v116, v116
	v_add_f32_e32 v118, 1.0, v118
	v_rcp_f32_e32 v118, v118
	v_mul_f32_e32 v116, v64, v116
	v_exp_f32_e32 v116, v116
	s_nop 0
	v_fma_f32 v121, -v116, v116, 1.0
	v_max_f32_e32 v121, 0, v121
	v_sqrt_f32_e32 v121, v121
	s_nop 0
	v_mul_f32_e32 v118, v118, v121
	v_mul_f32_e32 v114, v114, v118
	v_fmac_f32_e32 v114, v116, v115
	v_mul_f32_e32 v115, v120, v116
	v_fmamk_f32 v116, v117, 0xbfb8aa3b, v112
	v_exp_f32_e32 v116, v116
	v_fmamk_f32 v117, v119, 0xbfb8aa3b, v65
	v_exp_f32_e32 v117, v117
	v_add_f32_e32 v116, 1.0, v116
	v_rcp_f32_e32 v116, v116
	v_add_f32_e32 v117, 1.0, v117
	v_rcp_f32_e32 v117, v117
	v_mul_f32_e32 v116, v64, v116
	v_exp_f32_e32 v116, v116
	s_nop 0
	v_fma_f32 v118, -v116, v116, 1.0
	v_max_f32_e32 v118, 0, v118
	v_sqrt_f32_e32 v118, v118
	s_nop 0
	v_mul_f32_e32 v117, v117, v118
	v_mul_f32_e32 v113, v113, v117
	v_fmac_f32_e32 v113, v116, v114
	v_mul_f32_e32 v114, v115, v116
	v_add_u32_e32 v115, s14, v67
	v_readlane_b32 s22, v242, 62
	s_and_b32 s22, s22, 3
	s_cmp_lg_u32 s22, 3
	s_cbranch_scc1 .Lcvf_b_done
	s_cmp_lt_i32 s41, 0
	s_cbranch_scc1 .Lcvf_b_done
	s_waitcnt vmcnt(0)
	s_cmp_eq_u64 s[44:45], 0
	s_cbranch_scc1 .Lcvf_nogain
	v_mul_f32_e32 v186, v186, v218
	v_mul_f32_e32 v187, v187, v218
	v_mul_f32_e32 v188, v188, v218
	v_mul_f32_e32 v189, v189, v218
	v_mul_f32_e32 v190, v190, v219
	v_mul_f32_e32 v191, v191, v219
	v_mul_f32_e32 v192, v192, v219
	v_mul_f32_e32 v193, v193, v219
	v_mul_f32_e32 v194, v194, v220
	v_mul_f32_e32 v195, v195, v220
	v_mul_f32_e32 v196, v196, v220
	v_mul_f32_e32 v197, v197, v220
	v_mul_f32_e32 v198, v198, v221
	v_mul_f32_e32 v199, v199, v221
	v_mul_f32_e32 v200, v200, v221
	v_mul_f32_e32 v201, v201, v221
	v_mul_f32_e32 v202, v202, v222
	v_mul_f32_e32 v203, v203, v222
	v_mul_f32_e32 v204, v204, v222
	v_mul_f32_e32 v205, v205, v222
	v_mul_f32_e32 v206, v206, v223
	v_mul_f32_e32 v207, v207, v223
	v_mul_f32_e32 v208, v208, v223
	v_mul_f32_e32 v209, v209, v223
	v_mul_f32_e32 v210, v210, v224
	v_mul_f32_e32 v211, v211, v224
	v_mul_f32_e32 v212, v212, v224
	v_mul_f32_e32 v213, v213, v224
	v_mul_f32_e32 v214, v214, v225
	v_mul_f32_e32 v215, v215, v225
	v_mul_f32_e32 v216, v216, v225
	v_mul_f32_e32 v217, v217, v225
.Lcvf_nogain:
	s_cmp_eq_u32 s41, 0
	s_cbranch_scc1 .Lcvf_rowok
	v_and_b32_e32 v229, 0xffffff80, v227
	v_add_u32_e32 v227, v227, v229
	s_lshl_b32 s40, s41, 7
	s_add_i32 s40, s40, 0xffffff80
	v_add_u32_e32 v227, s40, v227
.Lcvf_rowok:
	s_lshl_b32 s40, s42, 1
	v_lshlrev_b32_e32 v226, 1, v226
	v_mad_u32_u24 v228, v227, s40, v226
	v_cvt_pk_bf16_f32 v230, v186, v190
	v_cvt_pk_bf16_f32 v231, v194, v198
	v_cvt_pk_bf16_f32 v232, v202, v206
	v_cvt_pk_bf16_f32 v233, v210, v214
	global_store_dwordx4 v228, v[230:233], s[48:49]
	v_add_u32_e32 v228, s40, v228
	s_nop 0
	v_cvt_pk_bf16_f32 v230, v187, v191
	v_cvt_pk_bf16_f32 v231, v195, v199
	v_cvt_pk_bf16_f32 v232, v203, v207
	v_cvt_pk_bf16_f32 v233, v211, v215
	global_store_dwordx4 v228, v[230:233], s[48:49]
	v_add_u32_e32 v228, s40, v228
	s_nop 0
	v_cvt_pk_bf16_f32 v230, v188, v192
	v_cvt_pk_bf16_f32 v231, v196, v200
	v_cvt_pk_bf16_f32 v232, v204, v208
	v_cvt_pk_bf16_f32 v233, v212, v216
	global_store_dwordx4 v228, v[230:233], s[48:49]
	v_add_u32_e32 v228, s40, v228
	s_nop 0
	v_cvt_pk_bf16_f32 v230, v189, v193
	v_cvt_pk_bf16_f32 v231, v197, v201
	v_cvt_pk_bf16_f32 v232, v205, v209
	v_cvt_pk_bf16_f32 v233, v213, v217
	global_store_dwordx4 v228, v[230:233], s[48:49]
.Lcvf_b_done:
	v_readlane_b32 s22, v242, 62
	s_add_i32 s22, s22, 1
	v_writelane_b32 v242, s22, 62
	s_andn2_b64 vcc, exec, s[50:51]
	ds_write2st64_b32 v115, v114, v113 offset1:1
	s_waitcnt lgkmcnt(0)
	s_barrier
	s_cbranch_vccnz .LBB0_122
	ds_read2st64_b32 v[114:115], v67 offset1:1
	ds_read2st64_b32 v[116:117], v67 offset0:2 offset1:3
	s_ashr_i32 s5, s4, 31
	s_lshl_b64 s[0:1], s[4:5], 14
	v_readlane_b32 s4, v243, 35
	s_waitcnt lgkmcnt(1)
	v_fma_f32 v113, 0, v114, v115
	s_waitcnt lgkmcnt(0)
	v_mul_f32_e32 v118, v114, v116
	ds_read2st64_b32 v[114:115], v67 offset0:4 offset1:5
	v_fmac_f32_e32 v117, v113, v116
	v_readlane_b32 s5, v243, 36
	s_add_u32 s0, s4, s0
	s_addc_u32 s1, s5, s1
	s_waitcnt lgkmcnt(0)
	v_fmac_f32_e32 v115, v117, v114
	ds_read2st64_b32 v[116:117], v67 offset0:6 offset1:7
	v_mul_f32_e32 v113, v118, v114
	s_lshl_b32 s4, s17, 2
	s_add_u32 s0, s0, s4
	s_addc_u32 s1, s1, 0
	s_waitcnt lgkmcnt(0)
	v_fmac_f32_e32 v117, v115, v116
	ds_read2st64_b32 v[114:115], v67 offset0:8 offset1:9
	v_mul_f32_e32 v113, v113, v116
	s_waitcnt lgkmcnt(0)
	v_fmac_f32_e32 v115, v117, v114
	ds_read2st64_b32 v[116:117], v67 offset0:10 offset1:11
	v_mul_f32_e32 v113, v113, v114
	s_waitcnt lgkmcnt(0)
	v_fmac_f32_e32 v117, v115, v116
	ds_read2st64_b32 v[114:115], v67 offset0:12 offset1:13
	v_mul_f32_e32 v113, v113, v116
	s_waitcnt lgkmcnt(0)
	v_fmac_f32_e32 v115, v117, v114
	ds_read2st64_b32 v[116:117], v67 offset0:14 offset1:15
	v_mul_f32_e32 v113, v113, v114
	s_waitcnt lgkmcnt(0)
	v_mul_f32_e32 v113, v113, v116
	v_fmac_f32_e32 v117, v115, v116
	global_store_dword v141, v113, s[0:1]
	global_store_dword v141, v117, s[0:1] offset:256
	s_branch .LBB0_122

.LBB0_150:
	s_cmp_gt_i32 s38, 2
	s_cselect_b64 s[0:1], -1, 0
	s_cmpk_gt_i32 s2, 0x17ff
	s_cselect_b64 s[4:5], -1, 0
	s_or_b64 s[0:1], s[0:1], s[4:5]
	s_and_b64 vcc, exec, s[0:1]
	s_branch .LBB0_172
	s_add_i32 s0, s38, 1
	s_mov_b32 s78, s38
	s_lshl_b32 s4, s0, 10
	v_readlane_b32 s36, v243, 62
	s_mul_i32 s6, s0, 0xf00000
	s_ashr_i32 s5, s4, 31
	v_readlane_b32 s48, v242, 10
	s_mul_hi_i32 s1, s0, 0xf00000
	s_mul_hi_i32 s13, s0, 0xb00000
	s_mul_i32 s12, s0, 0xb00000
	v_readlane_b32 s49, v242, 11
	s_add_u32 s0, s48, s6
	v_readlane_b32 s46, v242, 8
	s_addc_u32 s1, s49, s1
	s_lshl_b64 s[10:11], s[4:5], 2
	v_readlane_b32 s47, v242, 9
	s_add_u32 s4, s46, s10
	v_readlane_b32 s44, v242, 6
	s_addc_u32 s5, s47, s11
	v_readlane_b32 s45, v242, 7
	s_add_u32 s6, s44, s12
	v_readlane_b32 s42, v242, 4
	s_addc_u32 s7, s45, s13
	v_readlane_b32 s43, v242, 5
	s_add_u32 s8, s42, s12
	v_readlane_b32 s38, v242, 0
	s_addc_u32 s9, s43, s13
	v_readlane_b32 s39, v242, 1
	s_add_u32 s10, s38, s10
	v_readlane_b32 s40, v242, 2
	s_addc_u32 s11, s39, s11
	v_readlane_b32 s41, v242, 3
	s_add_u32 s12, s40, s12
	s_addc_u32 s13, s41, s13
	s_lshl_b32 s14, s2, 1
	s_lshl_b32 s16, s2, 5
	s_lshl_b32 s17, s86, 5
	s_lshl_b32 s18, s2, 6
	s_lshl_b32 s19, s86, 6
	s_add_i32 s20, s14, 0x1ea00
	s_lshl_b32 s21, s86, 1
	s_mov_b32 s22, s2
	v_readlane_b32 s37, v243, 63
	v_readlane_b32 s50, v242, 12
	v_readlane_b32 s51, v242, 13
	s_branch .LBB0_154
